# P3 kv-up epilogue: all epilogue loads (k-pe, k_norm_g, rope) issued at the start of the last k-step of the item GEMM into dead registers; epilogue only moves them into place
# baseline (speedup 1.0000x reference)
; DI unsigned pk_bf16(float lo, float hi) { f32x2v v = {lo, hi}; bf16x2v b = __builtin_convertvector(v, bf16x2v); return __builtin_bit_cast(unsigned, b); }
; DI bf16_t f2bf(float f) { return (bf16_t)(pk_bf16(f, 0.f) & 0xffffu); }
; DI int crow(int i, int hh) { return (i & 3) + 8 * (i >> 2) + 4 * hh; }
; DI void lds_sync() { wait_lgkm0(); bar_(); }
; DI void phase3(const Params& p, char* smem) {
;     ...
;       for (int tm = 0; tm < 4; ++tm)
; #pragma unroll
;         for (int i = 0; i < 16; ++i) { const float v = acc[tm][0][i] * ra; acc[tm][0][i] = v; if (tm < 2) ss += v * v; }
; #pragma unroll
;       for (int i = 0; i < 16; ++i) ss += kp[i] * kp[i];
;       ss += __shfl_xor(ss, 32);
;       const float rk = rsqrtf(ss * (1.f / QKD) + EPS);
; #pragma unroll
;       for (int i = 0; i < 16; ++i) kp[i] *= rk * p.k_norm_g[64 + crow(i, hh)];
;       if (lat) {
;         const int pos = key;
;         const float* tr = p.ropeTab + ((pos >> 6) * 8 + 4 * hh) * 2;
;         const float* tc = p.ropeTab + ((pos & 63) * 8 + 4 * hh) * 2;
; #pragma unroll
;         for (int i = 0; i < 4; ++i) { rope_pair(kp[i], kp[i + 4], tr + 2 * i); rope_pair(kp[8 + i], kp[12 + i], tc + 2 * i); }
;       }
;       {
;         char* kt_ = smem; char* vt_ = smem + 256 * 208;
;         char* kd = kt_ + tl * 208;
; #pragma unroll
;         for (int tm = 0; tm < 2; ++tm)
; #pragma unroll
;           for (int q = 0; q < 4; ++q) {
;             const int f = tm * 32 + 8 * q + 4 * hh;
;             const float4 g = *(const float4*)(p.k_norm_g + f);
;             uint2 o; o.x = pk_bf16(acc[tm][0][4 * q] * rk * g.x, acc[tm][0][4 * q + 1] * rk * g.y); o.y = pk_bf16(acc[tm][0][4 * q + 2] * rk * g.z, acc[tm][0][4 * q + 3] * rk * g.w);
;             *(uint2*)(kd + f * 2) = o;
;           }
; #pragma unroll
;         for (int q = 0; q < 4; ++q) {
;           uint2 o; o.x = pk_bf16(kp[4 * q], kp[4 * q + 1]); o.y = pk_bf16(kp[4 * q + 2], kp[4 * q + 3]);
;           *(uint2*)(kd + (64 + 8 * q + 4 * hh) * 2) = o;
;         }
; #pragma unroll
;         for (int tm = 2; tm < 4; ++tm)
; #pragma unroll
;           for (int i = 0; i < 16; ++i) *(bf16_t*)(vt_ + ((tm - 2) * 32 + crow(i, hh)) * 528 + tl * 2) = f2bf(acc[tm][0][i]);
;         lds_sync();
.LBB0_314:
	v_mov_b32_e32 v84, v146
	v_mov_b32_e32 v85, v147
	v_mov_b32_e32 v86, v148
	v_mov_b32_e32 v87, v149
	v_mov_b32_e32 v88, v150
	v_mov_b32_e32 v89, v151
	v_mov_b32_e32 v90, v152
	v_mov_b32_e32 v91, v153
	v_mov_b32_e32 v92, v154
	v_mov_b32_e32 v93, v155
	v_mov_b32_e32 v94, v156
	v_mov_b32_e32 v95, v157
	v_mov_b32_e32 v96, v222
	v_mov_b32_e32 v97, v223
	v_mov_b32_e32 v98, v224
	v_mov_b32_e32 v99, v225
	v_mov_b32_e32 v100, v226
	v_mov_b32_e32 v101, v227
	v_mov_b32_e32 v102, v228
	v_mov_b32_e32 v103, v229
	v_mov_b32_e32 v104, v230
	v_mov_b32_e32 v105, v231
	v_mov_b32_e32 v106, v232
	v_mov_b32_e32 v107, v233
	v_mov_b32_e32 v108, v234
	v_mov_b32_e32 v109, v235
	v_mov_b32_e32 v110, v236
	v_mov_b32_e32 v111, v237
	v_mov_b32_e32 v112, v238
	v_mov_b32_e32 v113, v239
	v_mov_b32_e32 v114, v240
	v_mov_b32_e32 v115, v241
	v_mov_b32_e32 v83, v82
	v_mul_f32_e32 v123, v0, v72
	v_mul_f32_e32 v124, v1, v72
	v_mul_f32_e32 v125, v2, v72
	v_mul_f32_e32 v126, v3, v72
	v_mul_f32_e32 v127, v4, v72
	v_mul_f32_e32 v128, v5, v72
	v_mul_f32_e32 v129, v6, v72
	v_mul_f32_e32 v130, v7, v72
	v_mul_f32_e32 v131, v8, v72
	v_mul_f32_e32 v132, v9, v72
	v_mul_f32_e32 v133, v10, v72
	v_mul_f32_e32 v134, v11, v72
	v_pk_mul_f32 v[0:1], v[48:49], v[82:83]
	v_pk_mul_f32 v[2:3], v[50:51], v[82:83]
	v_pk_mul_f32 v[4:5], v[52:53], v[82:83]
	v_pk_mul_f32 v[6:7], v[54:55], v[82:83]
	v_pk_mul_f32 v[8:9], v[56:57], v[82:83]
	v_pk_mul_f32 v[10:11], v[58:59], v[82:83]
	v_mul_f32_e32 v73, v16, v72
	v_mul_f32_e32 v116, v17, v72
	v_mul_f32_e32 v117, v18, v72
	v_mul_f32_e32 v118, v19, v72
	v_mul_f32_e32 v119, v20, v72
	v_mul_f32_e32 v120, v21, v72
	v_mul_f32_e32 v121, v22, v72
	v_mul_f32_e32 v122, v23, v72
	v_mul_f32_e32 v24, v24, v72
	v_mul_f32_e32 v25, v25, v72
	v_mul_f32_e32 v26, v26, v72
	v_mul_f32_e32 v27, v27, v72
	v_mul_f32_e32 v28, v28, v72
	v_mul_f32_e32 v29, v29, v72
	v_mul_f32_e32 v30, v30, v72
	v_mul_f32_e32 v31, v31, v72
	v_mul_f32_e32 v135, v12, v72
	v_mul_f32_e32 v136, v13, v72
	v_mul_f32_e32 v137, v14, v72
	v_mul_f32_e32 v72, v15, v72
	v_pk_mul_f32 v[12:13], v[60:61], v[82:83]
	v_pk_mul_f32 v[14:15], v[62:63], v[82:83]
	v_pk_mul_f32 v[16:17], v[64:65], v[82:83]
	v_pk_mul_f32 v[18:19], v[66:67], v[82:83]
	v_pk_mul_f32 v[20:21], v[68:69], v[82:83]
	v_pk_mul_f32 v[22:23], v[70:71], v[82:83]
	v_add_u32_e32 v138, v185, v187
	s_lshl_b32 s4, s90, 3
	s_or_b32 s6, s4, s57
	s_mul_i32 s5, s6, 0x900
	s_mul_hi_u32 s4, s6, 0x900
	s_add_u32 s5, s5, s42
	s_addc_u32 s4, s4, 0
	s_mulk_i32 s4, 0xc0
	s_mul_hi_u32 s7, s5, 0xc0
	s_add_i32 s7, s7, s4
	s_mulk_i32 s5, 0xc0
	s_add_u32 s4, s30, s5
	s_addc_u32 s5, s31, s7
	s_waitcnt vmcnt(7)
	v_pk_mul_f32 v[0:1], v[0:1], v[84:85]
	v_pk_mul_f32 v[2:3], v[2:3], v[86:87]
	s_waitcnt vmcnt(6)
	v_pk_mul_f32 v[4:5], v[4:5], v[88:89]
	v_pk_mul_f32 v[6:7], v[6:7], v[90:91]
	s_waitcnt vmcnt(5)
	v_pk_mul_f32 v[8:9], v[8:9], v[92:93]
	v_pk_mul_f32 v[10:11], v[10:11], v[94:95]
	s_waitcnt vmcnt(4)
	v_pk_mul_f32 v[12:13], v[12:13], v[96:97]
	v_pk_mul_f32 v[14:15], v[14:15], v[98:99]
	s_waitcnt vmcnt(3)
	v_pk_mul_f32 v[16:17], v[16:17], v[100:101]
	v_pk_mul_f32 v[18:19], v[18:19], v[102:103]
	s_waitcnt vmcnt(2)
	v_pk_mul_f32 v[20:21], v[20:21], v[104:105]
	v_pk_mul_f32 v[22:23], v[22:23], v[106:107]
	v_cvt_pk_bf16_f32 v0, v0, v1
	v_cvt_pk_bf16_f32 v1, v2, v3
	v_cvt_pk_bf16_f32 v2, v4, v5
	v_cvt_pk_bf16_f32 v3, v6, v7
	v_cvt_pk_bf16_f32 v4, v8, v9
	v_cvt_pk_bf16_f32 v5, v10, v11
	v_cvt_pk_bf16_f32 v6, v12, v13
	v_cvt_pk_bf16_f32 v7, v14, v15
	v_cvt_pk_bf16_f32 v8, v16, v17
	v_cvt_pk_bf16_f32 v9, v18, v19
	v_cvt_pk_bf16_f32 v10, v20, v21
	v_cvt_pk_bf16_f32 v11, v22, v23
	ds_write_b64 v207, v[2:3]
	ds_write_b64 v208, v[4:5]
	ds_write_b64 v209, v[6:7]
	ds_write_b64 v210, v[8:9]
	ds_write_b64 v211, v[10:11]
	v_pk_mul_f32 v[2:3], v[38:39], v[82:83]
	v_pk_mul_f32 v[4:5], v[36:37], v[82:83]
	s_waitcnt vmcnt(1)
	v_pk_mul_f32 v[2:3], v[2:3], v[108:109]
	v_pk_mul_f32 v[4:5], v[4:5], v[110:111]
	v_cvt_pk_bf16_f32 v2, v2, v3
	v_cvt_pk_bf16_f32 v3, v4, v5
	ds_write_b64 v212, v[2:3]
	v_pk_mul_f32 v[2:3], v[34:35], v[82:83]
	v_pk_mul_f32 v[4:5], v[32:33], v[82:83]
	s_waitcnt vmcnt(0)
	v_pk_mul_f32 v[2:3], v[2:3], v[112:113]
	v_pk_mul_f32 v[4:5], v[4:5], v[114:115]
	v_cvt_pk_bf16_f32 v2, v2, v3
	v_cvt_pk_bf16_f32 v3, v4, v5
	ds_write_b64 v213, v[2:3]
	v_cvt_pk_bf16_f32 v2, v76, v77
	v_cvt_pk_bf16_f32 v3, v78, v79
	ds_write2_b64 v138, v[0:1], v[2:3] offset1:16
	v_cvt_pk_bf16_f32 v0, v42, v43
	v_cvt_pk_bf16_f32 v1, v46, v47
	v_cvt_pk_bf16_f32 v2, v44, v45
	v_cvt_pk_bf16_f32 v3, v74, v75
	ds_write2_b64 v138, v[0:1], v[2:3] offset0:18 offset1:20
	v_cvt_pk_bf16_f32 v0, v40, v41
	v_cvt_pk_bf16_f32 v1, v80, v81
	ds_write_b64 v138, v[0:1] offset:176
	v_cvt_pk_bf16_f32 v0, v73, s0
	ds_write_b16 v204, v0 offset:53248
	v_cvt_pk_bf16_f32 v0, v116, s0
	ds_write_b16 v204, v0 offset:53776
	v_cvt_pk_bf16_f32 v0, v117, s0
	ds_write_b16 v204, v0 offset:54304
	v_cvt_pk_bf16_f32 v0, v118, s0
	ds_write_b16 v204, v0 offset:54832
	v_cvt_pk_bf16_f32 v0, v119, s0
	ds_write_b16 v204, v0 offset:57472
	v_cvt_pk_bf16_f32 v0, v120, s0
	ds_write_b16 v204, v0 offset:58000
	v_cvt_pk_bf16_f32 v0, v121, s0
	ds_write_b16 v204, v0 offset:58528
	v_cvt_pk_bf16_f32 v0, v122, s0
	ds_write_b16 v204, v0 offset:59056
	v_cvt_pk_bf16_f32 v0, v24, s0
	ds_write_b16 v204, v0 offset:61696
	v_cvt_pk_bf16_f32 v0, v25, s0
	ds_write_b16 v204, v0 offset:62224
	v_cvt_pk_bf16_f32 v0, v26, s0
	ds_write_b16 v204, v0 offset:62752
	v_cvt_pk_bf16_f32 v0, v27, s0
	ds_write_b16 v204, v0 offset:63280
	v_cvt_pk_bf16_f32 v0, v28, s0
	ds_write_b16 v205, v0 offset:12672
	v_cvt_pk_bf16_f32 v0, v29, s0
	ds_write_b16 v205, v0 offset:13200
	v_cvt_pk_bf16_f32 v0, v30, s0
	ds_write_b16 v205, v0 offset:13728
	v_cvt_pk_bf16_f32 v0, v31, s0
	ds_write_b16 v205, v0 offset:14256
	v_cvt_pk_bf16_f32 v0, v123, s0
	ds_write_b16 v205, v0 offset:16896
	v_cvt_pk_bf16_f32 v0, v124, s0
	ds_write_b16 v205, v0 offset:17424
	v_cvt_pk_bf16_f32 v0, v125, s0
	ds_write_b16 v205, v0 offset:17952
	v_cvt_pk_bf16_f32 v0, v126, s0
	ds_write_b16 v205, v0 offset:18480
	v_cvt_pk_bf16_f32 v0, v127, s0
	ds_write_b16 v205, v0 offset:21120
	v_cvt_pk_bf16_f32 v0, v128, s0
	ds_write_b16 v205, v0 offset:21648
	v_cvt_pk_bf16_f32 v0, v129, s0
	ds_write_b16 v205, v0 offset:22176
	v_cvt_pk_bf16_f32 v0, v130, s0
	ds_write_b16 v205, v0 offset:22704
	v_cvt_pk_bf16_f32 v0, v131, s0
	ds_write_b16 v205, v0 offset:25344
	v_cvt_pk_bf16_f32 v0, v132, s0
	ds_write_b16 v205, v0 offset:25872
	v_cvt_pk_bf16_f32 v0, v133, s0
	ds_write_b16 v205, v0 offset:26400
	v_cvt_pk_bf16_f32 v0, v134, s0
	ds_write_b16 v205, v0 offset:26928
	v_cvt_pk_bf16_f32 v0, v135, s0
	ds_write_b16 v205, v0 offset:29568
	v_cvt_pk_bf16_f32 v0, v136, s0
	ds_write_b16 v205, v0 offset:30096
	v_cvt_pk_bf16_f32 v0, v137, s0
	ds_write_b16 v205, v0 offset:30624
	v_cvt_pk_bf16_f32 v0, v72, s0
	ds_write_b16 v205, v0 offset:31152
	v_mov_b32_e32 v10, v220
	s_waitcnt lgkmcnt(0)
	s_barrier
; DI int tid_() { int t = threadIdx.x; asm volatile("" : "+v"(t)); return t; }
; DI void lds_sync() { wait_lgkm0(); bar_(); }
; DI void phase3(const Params& p, char* smem) {
;     ...
;         lds_sync();
;         const int tc_ = tid_();
;         bf16_t* Kg = p.K + ((size_t)(b * NH + hd) * NKEY + key0) * QKD;
; #pragma unroll
;         for (int i = 0; i < 6; ++i) {
;           const int id = tc_ + NTH * i, row = id / 12, ch = id % 12;
;           *(uint4*)(Kg + row * QKD + ch * 8) = *(const uint4*)(kt_ + row * 208 + ch * 16);
;         }
;         bf16_t* Vg = p.Vt + (size_t)(b * NH + hd) * VD * NKEY + key0;
; #pragma unroll
;         for (int i = 0; i < 4; ++i) {
;           const int row = (tc_ >> 5) + 16 * i, ch = tc_ & 31;
;           *(uint4*)(Vg + (size_t)row * NKEY + ch * 8) = *(const uint4*)(vt_ + row * 528 + ch * 16);
;         }
;         lds_sync();
	s_nop 0
	v_mul_hi_i32 v0, v10, s86
	v_lshrrev_b32_e32 v1, 31, v0
	v_ashrrev_i32_e32 v0, 1, v0
	v_add_u32_e32 v0, v0, v1
	v_mul_lo_u32 v1, v0, 12
	v_sub_u32_e32 v2, v10, v1
	v_mul_lo_u32 v1, v0, s65
	v_mul_lo_u32 v0, v0, s66
	v_lshl_add_u32 v4, v2, 4, v1
	v_ashrrev_i32_e32 v1, 31, v0
	v_lshlrev_b32_e32 v2, 3, v2
	v_lshl_add_u64 v[0:1], v[0:1], 1, s[4:5]
	v_ashrrev_i32_e32 v3, 31, v2
	v_lshl_add_u64 v[8:9], v[2:3], 1, v[0:1]
	ds_read_b128 v[0:3], v4
	v_add_u32_e32 v4, 0x200, v10
	v_mul_hi_i32 v5, v4, s86
	v_lshrrev_b32_e32 v6, 31, v5
	v_ashrrev_i32_e32 v5, 1, v5
	v_add_u32_e32 v11, v5, v6
	v_mul_lo_u32 v5, v11, 12
	v_sub_u32_e32 v12, v4, v5
	v_mul_lo_u32 v4, v11, s65
	v_lshl_add_u32 v4, v12, 4, v4
	ds_read_b128 v[4:7], v4
	s_waitcnt lgkmcnt(1)
	global_store_dwordx4 v[8:9], v[0:3], off
	v_ashrrev_i32_e32 v14, 5, v10
	s_nop 0
	v_mul_lo_u32 v0, v11, s66
	v_ashrrev_i32_e32 v1, 31, v0
	v_lshlrev_b32_e32 v2, 3, v12
	v_lshl_add_u64 v[0:1], v[0:1], 1, s[4:5]
	v_ashrrev_i32_e32 v3, 31, v2
	v_lshl_add_u64 v[0:1], v[2:3], 1, v[0:1]
	s_waitcnt lgkmcnt(0)
	global_store_dwordx4 v[0:1], v[4:7], off
	v_add_u32_e32 v0, 0x400, v10
	v_mul_hi_i32 v1, v0, s86
	v_lshrrev_b32_e32 v2, 31, v1
	v_ashrrev_i32_e32 v1, 1, v1
	v_add_u32_e32 v1, v1, v2
	v_mul_lo_u32 v2, v1, 12
	v_sub_u32_e32 v2, v0, v2
	v_mul_lo_u32 v0, v1, s65
	v_lshl_add_u32 v4, v2, 4, v0
	v_mul_lo_u32 v0, v1, s66
	v_ashrrev_i32_e32 v1, 31, v0
	v_lshlrev_b32_e32 v2, 3, v2
	v_lshl_add_u64 v[0:1], v[0:1], 1, s[4:5]
	v_ashrrev_i32_e32 v3, 31, v2
	v_lshl_add_u64 v[8:9], v[2:3], 1, v[0:1]
	ds_read_b128 v[0:3], v4
	v_add_u32_e32 v4, 0x600, v10
	v_mul_hi_i32 v5, v4, s86
	v_lshrrev_b32_e32 v6, 31, v5
	v_ashrrev_i32_e32 v5, 1, v5
	v_add_u32_e32 v11, v5, v6
	v_mul_lo_u32 v5, v11, 12
	v_sub_u32_e32 v12, v4, v5
	v_mul_lo_u32 v4, v11, s65
	v_lshl_add_u32 v4, v12, 4, v4
	ds_read_b128 v[4:7], v4
	s_waitcnt lgkmcnt(1)
	global_store_dwordx4 v[8:9], v[0:3], off
	s_nop 1
	v_mul_lo_u32 v0, v11, s66
	v_ashrrev_i32_e32 v1, 31, v0
	v_lshlrev_b32_e32 v2, 3, v12
	v_lshl_add_u64 v[0:1], v[0:1], 1, s[4:5]
	v_ashrrev_i32_e32 v3, 31, v2
	v_lshl_add_u64 v[0:1], v[2:3], 1, v[0:1]
	s_waitcnt lgkmcnt(0)
	global_store_dwordx4 v[0:1], v[4:7], off
	v_add_u32_e32 v0, 0x800, v10
	v_mul_hi_i32 v1, v0, s86
	v_lshrrev_b32_e32 v2, 31, v1
	v_ashrrev_i32_e32 v1, 1, v1
	v_add_u32_e32 v1, v1, v2
	v_mul_lo_u32 v2, v1, 12
	v_sub_u32_e32 v2, v0, v2
	v_mul_lo_u32 v0, v1, s65
	v_lshl_add_u32 v4, v2, 4, v0
	v_mul_lo_u32 v0, v1, s66
	v_ashrrev_i32_e32 v1, 31, v0
	v_lshlrev_b32_e32 v2, 3, v2
	v_lshl_add_u64 v[0:1], v[0:1], 1, s[4:5]
	v_ashrrev_i32_e32 v3, 31, v2
	v_lshl_add_u64 v[8:9], v[2:3], 1, v[0:1]
	ds_read_b128 v[0:3], v4
	v_add_u32_e32 v4, 0xa00, v10
	v_mul_hi_i32 v5, v4, s86
	v_lshrrev_b32_e32 v6, 31, v5
	v_ashrrev_i32_e32 v5, 1, v5
	v_add_u32_e32 v11, v5, v6
	v_mul_lo_u32 v5, v11, 12
	v_sub_u32_e32 v12, v4, v5
	v_mul_lo_u32 v4, v11, s65
	v_lshl_add_u32 v4, v12, 4, v4
	ds_read_b128 v[4:7], v4
	s_waitcnt lgkmcnt(1)
	global_store_dwordx4 v[8:9], v[0:3], off
	s_nop 1
	v_mul_lo_u32 v0, v11, s66
	v_ashrrev_i32_e32 v1, 31, v0
	v_lshlrev_b32_e32 v2, 3, v12
	v_lshl_add_u64 v[0:1], v[0:1], 1, s[4:5]
	v_ashrrev_i32_e32 v3, 31, v2
	s_mul_hi_u32 s4, s6, 0x48000
	s_mul_i32 s6, s6, 0x48000
	v_lshl_add_u64 v[0:1], v[2:3], 1, v[0:1]
	s_add_u32 s5, s40, s6
	s_waitcnt lgkmcnt(0)
	global_store_dwordx4 v[0:1], v[4:7], off
	s_addc_u32 s6, s41, s4
	s_lshl_b32 s4, s42, 1
	v_lshlrev_b32_e32 v0, 4, v10
	s_add_u32 s4, s5, s4
	v_and_b32_e32 v188, 0x1f0, v0
	s_addc_u32 s5, s6, 0
	v_mad_u64_u32 v[8:9], s[6:7], v14, s78, v[188:189]
	ds_read_b128 v[0:3], v8 offset:53248
	ds_read_b128 v[4:7], v8 offset:61696
	v_lshl_add_u64 v[10:11], s[4:5], 0, v[188:189]
	v_mad_i64_i32 v[12:13], s[4:5], v14, s88, v[10:11]
	s_waitcnt lgkmcnt(1)
	global_store_dwordx4 v[12:13], v[0:3], off
	s_nop 1
	v_add_u32_e32 v0, 16, v14
	v_mad_i64_i32 v[0:1], s[4:5], v0, s88, v[10:11]
	s_waitcnt lgkmcnt(0)
	global_store_dwordx4 v[0:1], v[4:7], off
	v_add_u32_e32 v0, 0x11200, v8
	ds_read_b128 v[0:3], v0
	v_add_u32_e32 v4, 32, v14
	v_mad_i64_i32 v[12:13], s[4:5], v4, s88, v[10:11]
	v_add_u32_e32 v4, 0x13300, v8
	ds_read_b128 v[4:7], v4
	s_waitcnt lgkmcnt(1)
	global_store_dwordx4 v[12:13], v[0:3], off
	s_nop 1
	v_add_u32_e32 v0, 48, v14
	v_mad_i64_i32 v[0:1], s[4:5], v0, s88, v[10:11]
	s_waitcnt lgkmcnt(0)
	global_store_dwordx4 v[0:1], v[4:7], off
	s_waitcnt lgkmcnt(0)
	s_barrier

; DI void wait_vm0() { asm volatile("s_waitcnt vmcnt(0)" ::: "memory"); }
; DI void bar_() { __builtin_amdgcn_s_barrier(); }
; #define GLDS(gp, lp) __builtin_amdgcn_global_load_lds((const unsigned*)(gp), (__attribute__((address_space(3))) unsigned*)(lp), 16, 0, 0)
; #define SB_ __builtin_amdgcn_sched_barrier(0)
; #define LOADF(A_, B_, ks) do { const int po_ = (((ks) * 2 + hh) ^ sw) * 16; \
;       _Pragma("unroll") for (int tm = 0; tm < TM; ++tm) A_[tm] = *(const bf16x8*)(As + tm * 32 * LDR + po_); \
;       _Pragma("unroll") for (int tn = 0; tn < TN; ++tn) B_[tn] = *(const bf16x8*)(Bs + tn * 32 * LDR + po_); } while (0)
; template <int TM, int TN, int WM, int WN, bool SUMSQ, int NST, class AF, class BF, class AFN, class BFN>
; DI void gemm8x(f32x16 (&acc)[TM][TN], AF arow, BF brow, int K, char* smem, float& sumsq, bool pre, bool hasNext, AFN arowN, BFN browN) {
;     ...
;     LOADF(a0, b0, 0);
;     LOADF(a1, b1, 1);
;     SB_;
;     if (issue) { if (a0v) GLDS(q0, l_); if (a1v) GLDS(q1, l_ + 8192); }
;     SB_;
;     __builtin_amdgcn_s_setprio(1);
;     MMF(a0, b0);
;     LOADF(a0, b0, 2);
;     SB_;
;     if (issue) { if (a2v) GLDS(q2, l_ + 16384); if (a3v) GLDS(q3, l_ + 24576); }
;     SB_;
;     MMF(a1, b1);
;     LOADF(a1, b1, 3);
;     SB_;
;     if (issue) { if (b0v) GLDS(s0, m_); if (b1v) GLDS(s1, m_ + 8192); }
;     SB_;
;     MMF(a0, b0);
;     SB_;
;     if (issue) { if (b2v) GLDS(s2, m_ + 16384); if (b3v) GLDS(s3, m_ + 24576); }
;     SB_;
;     MMF(a1, b1);
;     __builtin_amdgcn_s_setprio(0);
;   };
;   int sc_ = 0;
;   for (int kt = 0; kt < nk - 1; ++kt) {
;     SB_;
;     if (NST == 2) {
;       const int ko = (kt + 1) * 64;
;       compute(smem + (kt & 1) * STAGE, smem + ((kt + 1) & 1) * STAGE, true, pa0 + ko, pa1 + ko, pa2 + ko, pa3 + ko, pb0 + ko, pb1 + ko, pb2 + ko, pb3 + ko);
;       SB_;
;       wait_vm0(); bar_();
.LBB0_522:
	s_or_b64 exec, exec, s[6:7]
	v_lshlrev_b32_e32 v128, 16, v68
	v_and_b32_e32 v68, 0xffff0000, v68
	v_mul_f32_e32 v68, v68, v68
	v_lshlrev_b32_e32 v129, 16, v69
	v_fmac_f32_e32 v68, v128, v128
	v_and_b32_e32 v69, 0xffff0000, v69
	v_fmac_f32_e32 v68, v129, v129
	v_lshlrev_b32_e32 v130, 16, v70
	v_fmac_f32_e32 v68, v69, v69
	v_lshlrev_b32_e32 v69, 16, v64
	v_and_b32_e32 v64, 0xffff0000, v64
	v_and_b32_e32 v70, 0xffff0000, v70
	v_fmac_f32_e32 v68, v130, v130
	v_mul_f32_e32 v64, v64, v64
	v_lshlrev_b32_e32 v131, 16, v71
	v_fmac_f32_e32 v68, v70, v70
	v_lshlrev_b32_e32 v70, 16, v65
	v_fmac_f32_e32 v64, v69, v69
	v_and_b32_e32 v71, 0xffff0000, v71
	v_fmac_f32_e32 v68, v131, v131
	v_and_b32_e32 v65, 0xffff0000, v65
	v_fmac_f32_e32 v64, v70, v70
	v_fmac_f32_e32 v68, v71, v71
	v_lshlrev_b32_e32 v71, 16, v66
	v_fmac_f32_e32 v64, v65, v65
	v_and_b32_e32 v66, 0xffff0000, v66
	v_fmac_f32_e32 v64, v71, v71
	v_lshlrev_b32_e32 v128, 16, v67
	v_fmac_f32_e32 v64, v66, v66
	v_and_b32_e32 v66, 0xffff0000, v72
	v_and_b32_e32 v67, 0xffff0000, v67
	v_fmac_f32_e32 v64, v128, v128
	v_lshlrev_b32_e32 v65, 16, v72
	v_mul_f32_e32 v66, v66, v66
	v_fmac_f32_e32 v64, v67, v67
	v_lshlrev_b32_e32 v67, 16, v73
	v_fmac_f32_e32 v66, v65, v65
	v_add_f32_e32 v64, v68, v64
	v_and_b32_e32 v68, 0xffff0000, v73
	v_fmac_f32_e32 v66, v67, v67
	v_lshlrev_b32_e32 v69, 16, v74
	v_fmac_f32_e32 v66, v68, v68
	v_and_b32_e32 v70, 0xffff0000, v74
	v_fmac_f32_e32 v66, v69, v69
	v_lshlrev_b32_e32 v71, 16, v75
	v_fmac_f32_e32 v66, v70, v70
	v_and_b32_e32 v72, 0xffff0000, v75
	v_fmac_f32_e32 v66, v71, v71
	v_fmac_f32_e32 v66, v72, v72
	v_add_f32_e32 v64, v64, v66
	v_and_b32_e32 v66, 0xffff0000, v76
	v_lshlrev_b32_e32 v65, 16, v76
	v_mul_f32_e32 v66, v66, v66
	v_lshlrev_b32_e32 v67, 16, v77
	v_fmac_f32_e32 v66, v65, v65
	v_and_b32_e32 v68, 0xffff0000, v77
	v_fmac_f32_e32 v66, v67, v67
	v_lshlrev_b32_e32 v69, 16, v78
	v_fmac_f32_e32 v66, v68, v68
	v_and_b32_e32 v70, 0xffff0000, v78
	v_fmac_f32_e32 v66, v69, v69
	v_lshlrev_b32_e32 v71, 16, v79
	v_fmac_f32_e32 v66, v70, v70
	v_and_b32_e32 v72, 0xffff0000, v79
	v_fmac_f32_e32 v66, v71, v71
	v_fmac_f32_e32 v66, v72, v72
	v_add_f32_e32 v64, v64, v66
	v_and_b32_e32 v66, 0xffff0000, v84
	v_lshlrev_b32_e32 v65, 16, v84
	v_mul_f32_e32 v66, v66, v66
	v_lshlrev_b32_e32 v67, 16, v85
	v_fmac_f32_e32 v66, v65, v65
	v_and_b32_e32 v68, 0xffff0000, v85
	v_fmac_f32_e32 v66, v67, v67
	v_lshlrev_b32_e32 v69, 16, v86
	v_fmac_f32_e32 v66, v68, v68
	v_and_b32_e32 v70, 0xffff0000, v86
	v_fmac_f32_e32 v66, v69, v69
	v_lshlrev_b32_e32 v71, 16, v87
	v_fmac_f32_e32 v66, v70, v70
	v_and_b32_e32 v72, 0xffff0000, v87
	v_fmac_f32_e32 v66, v71, v71
	v_fmac_f32_e32 v66, v72, v72
	v_add_f32_e32 v64, v64, v66
	v_and_b32_e32 v66, 0xffff0000, v80
	v_lshlrev_b32_e32 v65, 16, v80
	v_mul_f32_e32 v66, v66, v66
	v_lshlrev_b32_e32 v67, 16, v81
	v_fmac_f32_e32 v66, v65, v65
	v_and_b32_e32 v68, 0xffff0000, v81
	v_fmac_f32_e32 v66, v67, v67
	v_lshlrev_b32_e32 v69, 16, v82
	v_fmac_f32_e32 v66, v68, v68
	v_and_b32_e32 v70, 0xffff0000, v82
	v_fmac_f32_e32 v66, v69, v69
	v_lshlrev_b32_e32 v71, 16, v83
	v_fmac_f32_e32 v66, v70, v70
	v_and_b32_e32 v72, 0xffff0000, v83
	v_fmac_f32_e32 v66, v71, v71
	v_fmac_f32_e32 v66, v72, v72
	v_add_f32_e32 v64, v64, v66
	v_and_b32_e32 v66, 0xffff0000, v88
	v_lshlrev_b32_e32 v65, 16, v88
	v_mul_f32_e32 v66, v66, v66
	v_lshlrev_b32_e32 v67, 16, v89
	v_fmac_f32_e32 v66, v65, v65
	v_and_b32_e32 v68, 0xffff0000, v89
	v_fmac_f32_e32 v66, v67, v67
	v_lshlrev_b32_e32 v69, 16, v90
	v_fmac_f32_e32 v66, v68, v68
	v_and_b32_e32 v70, 0xffff0000, v90
	v_fmac_f32_e32 v66, v69, v69
	v_lshlrev_b32_e32 v71, 16, v91
	v_fmac_f32_e32 v66, v70, v70
	v_and_b32_e32 v72, 0xffff0000, v91
	v_fmac_f32_e32 v66, v71, v71
	v_fmac_f32_e32 v66, v72, v72
	v_add_f32_e32 v64, v64, v66
	v_and_b32_e32 v66, 0xffff0000, v92
	v_lshlrev_b32_e32 v65, 16, v92
	v_mul_f32_e32 v66, v66, v66
	v_lshlrev_b32_e32 v67, 16, v93
	v_fmac_f32_e32 v66, v65, v65
	v_and_b32_e32 v68, 0xffff0000, v93
	v_fmac_f32_e32 v66, v67, v67
	v_lshlrev_b32_e32 v69, 16, v94
	v_fmac_f32_e32 v66, v68, v68
	v_and_b32_e32 v70, 0xffff0000, v94
	v_fmac_f32_e32 v66, v69, v69
	v_lshlrev_b32_e32 v71, 16, v95
	v_fmac_f32_e32 v66, v70, v70
	v_and_b32_e32 v72, 0xffff0000, v95
	v_fmac_f32_e32 v66, v71, v71
	v_fmac_f32_e32 v66, v72, v72
	v_add_f32_e32 v64, v64, v66
	v_and_b32_e32 v66, 0xffff0000, v124
	v_lshlrev_b32_e32 v65, 16, v124
	v_mul_f32_e32 v66, v66, v66
	v_lshlrev_b32_e32 v67, 16, v125
	v_fmac_f32_e32 v66, v65, v65
	v_and_b32_e32 v68, 0xffff0000, v125
	v_fmac_f32_e32 v66, v67, v67
	v_lshlrev_b32_e32 v69, 16, v126
	v_fmac_f32_e32 v66, v68, v68
	v_and_b32_e32 v70, 0xffff0000, v126
	v_fmac_f32_e32 v66, v69, v69
	v_lshlrev_b32_e32 v71, 16, v127
	v_fmac_f32_e32 v66, v70, v70
	v_and_b32_e32 v72, 0xffff0000, v127
	v_fmac_f32_e32 v66, v71, v71
	v_fmac_f32_e32 v66, v72, v72
	v_add_f32_e32 v64, v64, v66
	v_and_b32_e32 v66, 0xffff0000, v108
	v_lshlrev_b32_e32 v65, 16, v108
	v_mul_f32_e32 v66, v66, v66
	v_lshlrev_b32_e32 v67, 16, v109
	v_fmac_f32_e32 v66, v65, v65
	v_and_b32_e32 v68, 0xffff0000, v109
	v_fmac_f32_e32 v66, v67, v67
	v_lshlrev_b32_e32 v69, 16, v110
	v_fmac_f32_e32 v66, v68, v68
	v_and_b32_e32 v70, 0xffff0000, v110
	v_fmac_f32_e32 v66, v69, v69
	v_lshlrev_b32_e32 v71, 16, v111
	v_fmac_f32_e32 v66, v70, v70
	v_and_b32_e32 v72, 0xffff0000, v111
	v_fmac_f32_e32 v66, v71, v71
	v_fmac_f32_e32 v66, v72, v72
	v_add_f32_e32 v64, v64, v66
	v_and_b32_e32 v66, 0xffff0000, v120
	v_lshlrev_b32_e32 v65, 16, v120
	v_mul_f32_e32 v66, v66, v66
	v_lshlrev_b32_e32 v67, 16, v121
	v_fmac_f32_e32 v66, v65, v65
	v_and_b32_e32 v68, 0xffff0000, v121
	v_fmac_f32_e32 v66, v67, v67
	v_lshlrev_b32_e32 v69, 16, v122
	v_fmac_f32_e32 v66, v68, v68
	v_and_b32_e32 v70, 0xffff0000, v122
	v_fmac_f32_e32 v66, v69, v69
	v_lshlrev_b32_e32 v71, 16, v123
	v_fmac_f32_e32 v66, v70, v70
	v_and_b32_e32 v72, 0xffff0000, v123
	v_fmac_f32_e32 v66, v71, v71
	v_fmac_f32_e32 v66, v72, v72
	v_add_f32_e32 v66, v64, v66
	v_and_b32_e32 v65, 0xffff0000, v100
	v_lshlrev_b32_e32 v64, 16, v100
	v_mul_f32_e32 v69, v65, v65
	v_mfma_f32_32x32x16_bf16 v[48:63], v[116:119], v[100:103], v[48:63]
	v_lshlrev_b32_e32 v67, 16, v101
	v_fmac_f32_e32 v69, v64, v64
	v_and_b32_e32 v68, 0xffff0000, v101
	v_fmac_f32_e32 v69, v67, v67
	v_and_b32_e32 v64, 0xffff0000, v102
	v_lshlrev_b32_e32 v65, 16, v102
	v_fmac_f32_e32 v69, v68, v68
	v_mfma_f32_32x32x16_bf16 v[32:47], v[112:115], v[100:103], v[32:47]
	v_mul_f32_e64 v64, v64, v64
	v_mul_f32_e64 v65, v65, v65
	v_add_f32_e32 v65, v65, v69
	v_add_f32_e32 v67, v64, v65
	v_and_b32_e32 v64, 0xffff0000, v103
	v_lshlrev_b32_e32 v65, 16, v103
	v_pk_mul_f32 v[64:65], v[64:65], v[64:65]
	v_mfma_f32_32x32x16_bf16 v[16:31], v[104:107], v[100:103], v[16:31]
	v_add_f32_e32 v65, v65, v67
	v_add_f32_e32 v64, v64, v65
	v_add_f32_e32 v118, v66, v64
	v_mfma_f32_32x32x16_bf16 v[0:15], v[96:99], v[100:103], v[0:15]
	s_setprio 0
	s_waitcnt vmcnt(0)
	s_barrier
; template <int TM, int TN, int WM, int WN, bool SUMSQ, int NST, class AF, class BF, class AFN, class BFN>
; DI void gemm8x(f32x16 (&acc)[TM][TN], AF arow, BF brow, int K, char* smem, float& sumsq, bool pre, bool hasNext, AFN arowN, BFN browN) {
;     ...
;     LOADF(a0, b0, 0);
;     LOADF(a1, b1, 1);
;     SB_;
;     if (issue) { if (a0v) GLDS(q0, l_); if (a1v) GLDS(q1, l_ + 8192); }
;     SB_;
;     __builtin_amdgcn_s_setprio(1);
;     MMF(a0, b0);
;     LOADF(a0, b0, 2);
;     SB_;
;     if (issue) { if (a2v) GLDS(q2, l_ + 16384); if (a3v) GLDS(q3, l_ + 24576); }
;     SB_;
;     MMF(a1, b1);
;     LOADF(a1, b1, 3);
;     SB_;
;     if (issue) { if (b0v) GLDS(s0, m_); if (b1v) GLDS(s1, m_ + 8192); }
;     SB_;
;     MMF(a0, b0);
;     SB_;
;     if (issue) { if (b2v) GLDS(s2, m_ + 16384); if (b3v) GLDS(s3, m_ + 24576); }
;     SB_;
;     MMF(a1, b1);
;     __builtin_amdgcn_s_setprio(0);
; DI void phase3(const Params& p, char* smem) {
;     ...
; #pragma unroll
;       for (int q = 0; q < 4; ++q) {
;         const uint2 u = *(const uint2*)(kpeb + (size_t)tl * ldb + 8 * q + 4 * hh);
;         kp[4 * q + 0] = bf_lo(u.x); kp[4 * q + 1] = bf_hi(u.x); kp[4 * q + 2] = bf_lo(u.y); kp[4 * q + 3] = bf_hi(u.y);
;       }
;       float ss = 0.f;
; #pragma unroll
;       for (int tm = 0; tm < 4; ++tm)
; #pragma unroll
;         for (int i = 0; i < 16; ++i) { const float v = acc[tm][0][i] * ra; acc[tm][0][i] = v; if (tm < 2) ss += v * v; }
; #pragma unroll
;       for (int i = 0; i < 16; ++i) ss += kp[i] * kp[i];
;       ss += __shfl_xor(ss, 32);
;       const float rk = rsqrtf(ss * (1.f / QKD) + EPS);
; #pragma unroll
;       for (int i = 0; i < 16; ++i) kp[i] *= rk * p.k_norm_g[64 + crow(i, hh)];
;       if (lat) {
;         const int pos = key;
;         const float* tr = p.ropeTab + ((pos >> 6) * 8 + 4 * hh) * 2;
;         const float* tc = p.ropeTab + ((pos & 63) * 8 + 4 * hh) * 2;
; #pragma unroll
;         for (int i = 0; i < 4; ++i) { rope_pair(kp[i], kp[i + 4], tr + 2 * i); rope_pair(kp[8 + i], kp[12 + i], tc + 2 * i); }
;       }
;       {
;         char* kt_ = smem; char* vt_ = smem + 256 * 208;
;         char* kd = kt_ + tl * 208;
; #pragma unroll
;         for (int tm = 0; tm < 2; ++tm)
; #pragma unroll
;           for (int q = 0; q < 4; ++q) {
;             const int f = tm * 32 + 8 * q + 4 * hh;
;             const float4 g = *(const float4*)(p.k_norm_g + f);
	v_mul_lo_u32 v215, s56, v184
	v_add_lshl_u32 v215, v215, v186, 1
	global_load_dwordx2 v[216:217], v215, s[16:17]
	global_load_dwordx2 v[218:219], v215, s[16:17] offset:16
	global_load_dwordx2 v[158:159], v215, s[16:17] offset:32
	global_load_dwordx2 v[250:251], v215, s[16:17] offset:48
	global_load_dwordx4 v[176:179], v[194:195], off offset:320
	global_load_dwordx4 v[180:183], v[194:195], off offset:352
	global_load_dwordx4 v[196:199], v[194:195], off offset:256
	global_load_dwordx4 v[200:203], v[194:195], off offset:288
	v_add_u32_e32 v215, s42, v184
	v_ashrrev_i32_e32 v215, 3, v215
	v_and_or_b32 v215, v215, s85, v186
	v_lshlrev_b32_e32 v215, 3, v215
	global_load_dwordx4 v[242:245], v[192:193], off
	global_load_dwordx4 v[246:249], v[192:193], off offset:16
	global_load_dwordx4 v[168:171], v215, s[38:39]
	global_load_dwordx4 v[172:175], v215, s[38:39] offset:16
	global_load_dwordx4 v[146:149], v[194:195], off
	global_load_dwordx4 v[150:153], v[194:195], off offset:32
	global_load_dwordx4 v[154:157], v[194:195], off offset:64
	global_load_dwordx4 v[222:225], v[194:195], off offset:96
	global_load_dwordx4 v[226:229], v[194:195], off offset:128
	global_load_dwordx4 v[230:233], v[194:195], off offset:160
	global_load_dwordx4 v[234:237], v[194:195], off offset:192
	global_load_dwordx4 v[238:241], v[194:195], off offset:224
	ds_read_b128 v[64:67], v162 offset:49152
	ds_read_b128 v[68:71], v162 offset:53248
	ds_read_b128 v[72:75], v162 offset:57344
	ds_read_b128 v[76:79], v162 offset:61440
	ds_read_b128 v[80:83], v165 offset:16384
	ds_read_b128 v[84:87], v163 offset:49152
	ds_read_b128 v[88:91], v163 offset:53248
	ds_read_b128 v[92:95], v163 offset:57344
	ds_read_b128 v[96:99], v163 offset:61440
	ds_read_b128 v[100:103], v166 offset:16384
	s_setprio 1
	s_waitcnt lgkmcnt(0)
	v_mfma_f32_32x32x16_bf16 v[48:63], v[64:67], v[80:83], v[48:63]
	v_mfma_f32_32x32x16_bf16 v[32:47], v[68:71], v[80:83], v[32:47]
	v_mfma_f32_32x32x16_bf16 v[16:31], v[72:75], v[80:83], v[16:31]
	ds_read_b128 v[64:67], v161 offset:49152
	ds_read_b128 v[68:71], v161 offset:53248
	ds_read_b128 v[72:75], v161 offset:57344
	ds_read_b128 v[104:107], v161 offset:61440
	ds_read_b128 v[108:111], v167 offset:16384
	v_mfma_f32_32x32x16_bf16 v[0:15], v[76:79], v[80:83], v[0:15]
	v_and_b32_e32 v79, 0xffff0000, v100
	v_and_b32_e32 v78, 0xffff0000, v80
	v_lshlrev_b32_e32 v77, 16, v100
	v_lshlrev_b32_e32 v76, 16, v80
	v_mul_f32_e64 v78, v78, v78
	v_mul_f32_e64 v79, v79, v79
	v_lshlrev_b32_e32 v113, 16, v101
	v_lshlrev_b32_e32 v112, 16, v81
	v_pk_fma_f32 v[76:77], v[76:77], v[76:77], v[78:79]
	v_and_b32_e32 v115, 0xffff0000, v101
	v_and_b32_e32 v114, 0xffff0000, v81
	v_pk_fma_f32 v[76:77], v[112:113], v[112:113], v[76:77]
	v_lshlrev_b32_e32 v81, 16, v102
	v_lshlrev_b32_e32 v80, 16, v82
	v_pk_fma_f32 v[76:77], v[114:115], v[114:115], v[76:77]
	v_mfma_f32_32x32x16_bf16 v[48:63], v[84:87], v[100:103], v[48:63]
	v_and_b32_e32 v85, 0xffff0000, v102
	v_and_b32_e32 v84, 0xffff0000, v82
	v_fma_f32 v76, v80, v80, v76
	v_fma_f32 v77, v81, v81, v77
	v_lshlrev_b32_e32 v87, 16, v103
	v_lshlrev_b32_e32 v86, 16, v83
	v_pk_fma_f32 v[76:77], v[84:85], v[84:85], v[76:77]
	v_and_b32_e32 v117, 0xffff0000, v103
	v_and_b32_e32 v116, 0xffff0000, v83
	v_pk_fma_f32 v[76:77], v[86:87], v[86:87], v[76:77]
	v_mfma_f32_32x32x16_bf16 v[32:47], v[88:91], v[100:103], v[32:47]
	v_fma_f32 v76, v116, v116, v76
	v_fma_f32 v77, v117, v117, v77
	v_add_f32_e32 v76, v118, v76
	v_add_f32_e32 v112, v76, v77
	v_mfma_f32_32x32x16_bf16 v[16:31], v[92:95], v[100:103], v[16:31]
	ds_read_b128 v[76:79], v160 offset:49152
	ds_read_b128 v[80:83], v160 offset:53248
	ds_read_b128 v[84:87], v160 offset:57344
	ds_read_b128 v[88:91], v160 offset:61440
	ds_read_b128 v[92:95], v164 offset:16384
	v_mfma_f32_32x32x16_bf16 v[0:15], v[96:99], v[100:103], v[0:15]
	s_waitcnt lgkmcnt(0)
	v_mfma_f32_32x32x16_bf16 v[48:63], v[64:67], v[108:111], v[48:63]
	v_mfma_f32_32x32x16_bf16 v[32:47], v[68:71], v[108:111], v[32:47]
	v_mfma_f32_32x32x16_bf16 v[16:31], v[72:75], v[108:111], v[16:31]
	v_mfma_f32_32x32x16_bf16 v[0:15], v[104:107], v[108:111], v[0:15]
	v_and_b32_e32 v67, 0xffff0000, v92
	v_and_b32_e32 v66, 0xffff0000, v108
	v_lshlrev_b32_e32 v64, 16, v108
	v_lshlrev_b32_e32 v65, 16, v92
	v_mul_f32_e64 v66, v66, v66
	v_mul_f32_e64 v67, v67, v67
	v_lshlrev_b32_e32 v68, 16, v109
	v_lshlrev_b32_e32 v69, 16, v93
	v_pk_fma_f32 v[64:65], v[64:65], v[64:65], v[66:67]
	v_mfma_f32_32x32x16_bf16 v[48:63], v[76:79], v[92:95], v[48:63]
	v_and_b32_e32 v71, 0xffff0000, v93
	v_and_b32_e32 v70, 0xffff0000, v109
	v_fma_f32 v64, v68, v68, v64
	v_fma_f32 v65, v69, v69, v65
	v_lshlrev_b32_e32 v72, 16, v110
	v_lshlrev_b32_e32 v73, 16, v94
	v_pk_fma_f32 v[64:65], v[70:71], v[70:71], v[64:65]
	v_and_b32_e32 v75, 0xffff0000, v94
	v_mfma_f32_32x32x16_bf16 v[32:47], v[80:83], v[92:95], v[32:47]
	v_and_b32_e32 v74, 0xffff0000, v110
	v_fma_f32 v64, v72, v72, v64
	v_fma_f32 v65, v73, v73, v65
	v_lshlrev_b32_e32 v76, 16, v111
	v_lshlrev_b32_e32 v77, 16, v95
	v_pk_fma_f32 v[64:65], v[74:75], v[74:75], v[64:65]
	v_and_b32_e32 v79, 0xffff0000, v95
	v_and_b32_e32 v78, 0xffff0000, v111
	v_mfma_f32_32x32x16_bf16 v[16:31], v[84:87], v[92:95], v[16:31]
	v_fma_f32 v64, v76, v76, v64
	v_fma_f32 v65, v77, v77, v65
	v_fma_f32 v64, v78, v78, v64
	v_fma_f32 v65, v79, v79, v65
	v_add_f32_e32 v64, v112, v64
	v_add_f32_e32 v66, v64, v65
	v_mfma_f32_32x32x16_bf16 v[0:15], v[88:91], v[92:95], v[0:15]
	s_setprio 0
	v_mad_i64_i32 v[64:65], s[4:5], s56, v184, 0
	v_lshl_add_u64 v[64:65], v[64:65], 1, s[16:17]
	v_lshlrev_b32_e32 v188, 1, v186
	v_lshl_add_u64 v[64:65], v[64:65], 0, v[188:189]
	s_waitcnt lgkmcnt(0)
	s_barrier
; DI float bf_lo(unsigned u) { return __uint_as_float(u << 16); }
; DI float bf_hi(unsigned u) { return __uint_as_float(u & 0xffff0000u); }
; DI int crow(int i, int hh) { return (i & 3) + 8 * (i >> 2) + 4 * hh; }
; DI void phase3(const Params& p, char* smem) {
;     ...
;       sumsq += __shfl_xor(sumsq, 32);
;       const float ra = rsqrtf(sumsq * (1.f / KVL) + EPS);
;       const int tl = w * 32 + r;
;       const int key = key0 + tl;
;       float kp[16];
; #pragma unroll
;       for (int q = 0; q < 4; ++q) {
;         const uint2 u = *(const uint2*)(kpeb + (size_t)tl * ldb + 8 * q + 4 * hh);
;         kp[4 * q + 0] = bf_lo(u.x); kp[4 * q + 1] = bf_hi(u.x); kp[4 * q + 2] = bf_lo(u.y); kp[4 * q + 3] = bf_hi(u.y);
;       }
;       float ss = 0.f;
; #pragma unroll
;       for (int tm = 0; tm < 4; ++tm)
; #pragma unroll
;         for (int i = 0; i < 16; ++i) { const float v = acc[tm][0][i] * ra; acc[tm][0][i] = v; if (tm < 2) ss += v * v; }
; #pragma unroll
;       for (int i = 0; i < 16; ++i) ss += kp[i] * kp[i];
;       ss += __shfl_xor(ss, 32);
;       const float rk = rsqrtf(ss * (1.f / QKD) + EPS);
; #pragma unroll
;       for (int i = 0; i < 16; ++i) kp[i] *= rk * p.k_norm_g[64 + crow(i, hh)];
	v_and_b32_e32 v65, 64, v214
	v_xor_b32_e32 v64, 32, v214
	v_add_u32_e32 v65, 64, v65
	v_cmp_lt_i32_e32 vcc, v64, v65
	v_cndmask_b32_e32 v64, v214, v64, vcc
	v_lshlrev_b32_e32 v73, 2, v64
	ds_bpermute_b32 v64, v73, v66
	s_waitcnt lgkmcnt(0)
	v_add_f32_e32 v64, v66, v64
	v_fmamk_f32 v64, v64, 0x3b800000, v206
	v_mul_f32_e32 v65, 0x4b800000, v64
	v_cmp_gt_f32_e32 vcc, s84, v64
	s_waitcnt vmcnt(0)
	v_mov_b32_e32 v74, v216
	v_mov_b32_e32 v75, v217
	v_mov_b32_e32 v80, v218
	v_mov_b32_e32 v81, v219
	v_mov_b32_e32 v82, v158
	v_mov_b32_e32 v83, v159
	v_mov_b32_e32 v96, v250
	v_mov_b32_e32 v97, v251
	v_mov_b32_e32 v84, v176
	v_mov_b32_e32 v85, v177
	v_mov_b32_e32 v86, v178
	v_mov_b32_e32 v87, v179
	v_mov_b32_e32 v88, v180
	v_mov_b32_e32 v89, v181
	v_mov_b32_e32 v90, v182
	v_mov_b32_e32 v91, v183
	v_mov_b32_e32 v76, v196
	v_mov_b32_e32 v77, v197
	v_mov_b32_e32 v78, v198
	v_mov_b32_e32 v79, v199
	v_mov_b32_e32 v92, v200
	v_mov_b32_e32 v93, v201
	v_mov_b32_e32 v94, v202
	v_mov_b32_e32 v95, v203
	v_lshlrev_b32_e32 v122, 16, v74
	v_cndmask_b32_e32 v64, v64, v65, vcc
	v_rsq_f32_e32 v64, v64
	v_and_b32_e32 v123, 0xffff0000, v74
	v_pk_mul_f32 v[142:143], v[122:123], v[122:123]
	v_lshlrev_b32_e32 v74, 16, v75
	v_mul_f32_e32 v65, 0x45800000, v64
	v_cndmask_b32_e32 v72, v64, v65, vcc
	v_pk_mul_f32 v[48:49], v[48:49], v[72:73] op_sel_hi:[1,0]
	v_pk_mul_f32 v[50:51], v[50:51], v[72:73] op_sel_hi:[1,0]
	v_pk_mul_f32 v[70:71], v[38:39], v[72:73] op_sel_hi:[1,0]
	v_pk_mul_f32 v[38:39], v[40:41], v[72:73] op_sel_hi:[1,0]
	v_pk_mul_f32 v[40:41], v[48:49], v[48:49]
	v_pk_mul_f32 v[68:69], v[36:37], v[72:73] op_sel_hi:[1,0]
	v_pk_mul_f32 v[36:37], v[42:43], v[72:73] op_sel_hi:[1,0]
	v_pk_mul_f32 v[42:43], v[50:51], v[50:51]
	v_add_f32_e32 v40, v40, v41
	v_pk_mul_f32 v[52:53], v[52:53], v[72:73] op_sel_hi:[1,0]
	v_add_f32_e32 v40, v42, v40
	v_pk_mul_f32 v[66:67], v[34:35], v[72:73] op_sel_hi:[1,0]
	v_pk_mul_f32 v[34:35], v[44:45], v[72:73] op_sel_hi:[1,0]
	v_pk_mul_f32 v[44:45], v[52:53], v[52:53]
	v_add_f32_e32 v40, v43, v40
	v_pk_mul_f32 v[54:55], v[54:55], v[72:73] op_sel_hi:[1,0]
	v_add_f32_e32 v40, v44, v40
	v_pk_mul_f32 v[64:65], v[32:33], v[72:73] op_sel_hi:[1,0]
	v_pk_mul_f32 v[32:33], v[46:47], v[72:73] op_sel_hi:[1,0]
	v_pk_mul_f32 v[46:47], v[54:55], v[54:55]
	v_add_f32_e32 v40, v45, v40
	v_pk_mul_f32 v[56:57], v[56:57], v[72:73] op_sel_hi:[1,0]
	v_add_f32_e32 v40, v46, v40
	v_pk_mul_f32 v[98:99], v[56:57], v[56:57]
	v_add_f32_e32 v40, v47, v40
	v_pk_mul_f32 v[58:59], v[58:59], v[72:73] op_sel_hi:[1,0]
	v_add_f32_e32 v40, v98, v40
	v_pk_mul_f32 v[100:101], v[58:59], v[58:59]
	v_add_f32_e32 v40, v99, v40
	v_pk_mul_f32 v[60:61], v[60:61], v[72:73] op_sel_hi:[1,0]
	v_add_f32_e32 v40, v100, v40
	v_pk_mul_f32 v[102:103], v[60:61], v[60:61]
	v_add_f32_e32 v40, v101, v40
	v_pk_mul_f32 v[62:63], v[62:63], v[72:73] op_sel_hi:[1,0]
	v_add_f32_e32 v40, v102, v40
	v_pk_mul_f32 v[104:105], v[62:63], v[62:63]
	v_add_f32_e32 v40, v103, v40
	v_add_f32_e32 v40, v104, v40
	v_pk_mul_f32 v[106:107], v[64:65], v[64:65]
	v_add_f32_e32 v40, v105, v40
	v_add_f32_e32 v40, v106, v40
	v_pk_mul_f32 v[108:109], v[66:67], v[66:67]
	v_add_f32_e32 v40, v107, v40
	v_add_f32_e32 v40, v108, v40
	v_pk_mul_f32 v[110:111], v[68:69], v[68:69]
	v_add_f32_e32 v40, v109, v40
	v_add_f32_e32 v40, v110, v40
	v_pk_mul_f32 v[112:113], v[70:71], v[70:71]
	v_add_f32_e32 v40, v111, v40
	v_add_f32_e32 v40, v112, v40
	v_pk_mul_f32 v[114:115], v[38:39], v[38:39]
	v_add_f32_e32 v40, v113, v40
	v_add_f32_e32 v40, v114, v40
	v_pk_mul_f32 v[116:117], v[36:37], v[36:37]
	v_add_f32_e32 v40, v115, v40
	v_add_f32_e32 v40, v116, v40
	v_pk_mul_f32 v[118:119], v[34:35], v[34:35]
	v_add_f32_e32 v40, v117, v40
	v_add_f32_e32 v40, v118, v40
	v_pk_mul_f32 v[120:121], v[32:33], v[32:33]
	v_add_f32_e32 v40, v119, v40
	v_add_f32_e32 v40, v120, v40
	v_add_f32_e32 v40, v121, v40
	v_and_b32_e32 v75, 0xffff0000, v75
	v_add_f32_e32 v40, v142, v40
	v_pk_mul_f32 v[138:139], v[74:75], v[74:75]
	v_add_f32_e32 v40, v143, v40
	v_lshlrev_b32_e32 v124, 16, v80
	v_and_b32_e32 v125, 0xffff0000, v80
	v_add_f32_e32 v40, v138, v40
	v_pk_mul_f32 v[144:145], v[124:125], v[124:125]
	v_add_f32_e32 v40, v139, v40
	v_lshlrev_b32_e32 v80, 16, v81
	v_and_b32_e32 v81, 0xffff0000, v81
	v_add_f32_e32 v40, v144, v40
	v_pk_mul_f32 v[140:141], v[80:81], v[80:81]
	v_add_f32_e32 v40, v145, v40
	v_lshlrev_b32_e32 v126, 16, v82
	v_and_b32_e32 v127, 0xffff0000, v82
	v_add_f32_e32 v40, v140, v40
	v_pk_mul_f32 v[134:135], v[126:127], v[126:127]
	v_add_f32_e32 v40, v141, v40
	v_lshlrev_b32_e32 v128, 16, v83
	v_and_b32_e32 v129, 0xffff0000, v83
	v_add_f32_e32 v40, v134, v40
	v_pk_mul_f32 v[82:83], v[128:129], v[128:129]
	v_add_f32_e32 v40, v135, v40
	v_lshlrev_b32_e32 v130, 16, v96
	v_and_b32_e32 v131, 0xffff0000, v96
	v_add_f32_e32 v40, v82, v40
	v_pk_mul_f32 v[136:137], v[130:131], v[130:131]
	v_add_f32_e32 v40, v83, v40
	v_lshlrev_b32_e32 v96, 16, v97
	v_and_b32_e32 v97, 0xffff0000, v97
	v_add_f32_e32 v40, v136, v40
	v_pk_mul_f32 v[132:133], v[96:97], v[96:97]
	v_add_f32_e32 v40, v137, v40
	v_add_f32_e32 v40, v132, v40
	v_add_f32_e32 v40, v133, v40
	ds_bpermute_b32 v41, v73, v40
	s_waitcnt lgkmcnt(0)
	v_add_f32_e32 v40, v40, v41
	v_fmamk_f32 v40, v40, 0x3c2aaaab, v206
	v_mul_f32_e32 v41, 0x4b800000, v40
	v_cmp_gt_f32_e32 vcc, s84, v40
	s_nop 1
	v_cndmask_b32_e32 v40, v40, v41, vcc
	v_rsq_f32_e32 v40, v40
	s_nop 0
	v_mul_f32_e32 v41, 0x45800000, v40
	v_cndmask_b32_e32 v82, v40, v41, vcc
	v_pk_mul_f32 v[40:41], v[76:77], v[82:83] op_sel_hi:[1,0]
	s_andn2_b64 vcc, exec, s[14:15]
	v_pk_mul_f32 v[76:77], v[40:41], v[122:123]
	v_pk_mul_f32 v[40:41], v[78:79], v[82:83] op_sel_hi:[1,0]
	s_nop 0
	v_pk_mul_f32 v[78:79], v[40:41], v[74:75]
	v_pk_mul_f32 v[40:41], v[92:93], v[82:83] op_sel_hi:[1,0]
	s_nop 0
	v_pk_mul_f32 v[42:43], v[40:41], v[124:125]
	v_pk_mul_f32 v[40:41], v[94:95], v[82:83] op_sel_hi:[1,0]
	s_nop 0
	v_pk_mul_f32 v[46:47], v[40:41], v[80:81]
	v_pk_mul_f32 v[40:41], v[84:85], v[82:83] op_sel_hi:[1,0]
	v_pk_mul_f32 v[80:81], v[90:91], v[82:83] op_sel_hi:[1,0]
	v_pk_mul_f32 v[44:45], v[40:41], v[126:127]
	v_pk_mul_f32 v[40:41], v[86:87], v[82:83] op_sel_hi:[1,0]
	v_pk_mul_f32 v[80:81], v[80:81], v[96:97]
	v_pk_mul_f32 v[74:75], v[40:41], v[128:129]
	v_pk_mul_f32 v[40:41], v[88:89], v[82:83] op_sel_hi:[1,0]
	s_nop 0
	v_pk_mul_f32 v[40:41], v[40:41], v[130:131]
	s_cbranch_vccnz .LBB0_314
; DI void phase3(const Params& p, char* smem) {
;     ...
;       if (lat) {
;         const int pos = key;
;         const float* tr = p.ropeTab + ((pos >> 6) * 8 + 4 * hh) * 2;
;         const float* tc = p.ropeTab + ((pos & 63) * 8 + 4 * hh) * 2;
; #pragma unroll
;         for (int i = 0; i < 4; ++i) { rope_pair(kp[i], kp[i + 4], tr + 2 * i); rope_pair(kp[8 + i], kp[12 + i], tc + 2 * i); }
;       }
	v_add_u32_e32 v73, s42, v184
	v_ashrrev_i32_e32 v73, 3, v73
	v_and_or_b32 v73, v73, s85, v186
	v_lshlrev_b32_e32 v92, 1, v73
	v_ashrrev_i32_e32 v93, 31, v92
	v_mov_b32_e32 v84, v242
	v_mov_b32_e32 v85, v243
	v_mov_b32_e32 v86, v244
	v_mov_b32_e32 v87, v245
	v_mov_b32_e32 v88, v246
	v_mov_b32_e32 v89, v247
	v_mov_b32_e32 v90, v248
	v_mov_b32_e32 v91, v249
	v_lshl_add_u64 v[96:97], v[92:93], 2, s[38:39]
	v_mov_b32_e32 v92, v168
	v_mov_b32_e32 v93, v169
	v_mov_b32_e32 v94, v170
	v_mov_b32_e32 v95, v171
	s_nop 0
	v_mov_b32_e32 v96, v172
	v_mov_b32_e32 v97, v173
	v_mov_b32_e32 v98, v174
	v_mov_b32_e32 v99, v175
	s_waitcnt vmcnt(3)
	v_mov_b32_e32 v101, v86
	v_mov_b32_e32 v86, v85
	v_mov_b32_e32 v100, v84
	s_waitcnt vmcnt(2)
	v_mov_b32_e32 v84, v88
	v_mov_b32_e32 v85, v90
	v_mov_b32_e32 v90, v89
	v_pk_mul_f32 v[88:89], v[44:45], v[86:87]
	v_pk_mul_f32 v[86:87], v[40:41], v[86:87]
	v_pk_mul_f32 v[102:103], v[74:75], v[90:91]
	v_pk_mul_f32 v[90:91], v[80:81], v[90:91]
	v_pk_fma_f32 v[44:45], v[44:45], v[100:101], v[86:87] neg_lo:[0,0,1] neg_hi:[0,0,1]
	v_pk_fma_f32 v[40:41], v[40:41], v[100:101], v[88:89]
	s_waitcnt vmcnt(1)
	v_mov_b32_e32 v87, v94
	v_mov_b32_e32 v94, v93
	s_waitcnt vmcnt(0)
	v_mov_b32_e32 v89, v98
	v_mov_b32_e32 v98, v97
	v_pk_fma_f32 v[74:75], v[74:75], v[84:85], v[90:91] neg_lo:[0,0,1] neg_hi:[0,0,1]
	v_mov_b32_e32 v86, v92
	v_mov_b32_e32 v88, v96
	v_pk_mul_f32 v[90:91], v[76:77], v[94:95]
	v_pk_mul_f32 v[92:93], v[42:43], v[94:95]
	v_pk_mul_f32 v[94:95], v[78:79], v[98:99]
	v_pk_mul_f32 v[96:97], v[46:47], v[98:99]
	v_pk_fma_f32 v[76:77], v[76:77], v[86:87], v[92:93] neg_lo:[0,0,1] neg_hi:[0,0,1]
	v_pk_fma_f32 v[42:43], v[42:43], v[86:87], v[90:91]
	v_pk_fma_f32 v[78:79], v[78:79], v[88:89], v[96:97] neg_lo:[0,0,1] neg_hi:[0,0,1]
	v_pk_fma_f32 v[46:47], v[46:47], v[88:89], v[94:95]
	v_pk_fma_f32 v[80:81], v[80:81], v[84:85], v[102:103]
	s_branch .LBB0_314
